# C + P4 loop-edge edit (7.12): wave-uniform rescale test fed directly by the v_cmp mask, canonicalising v_max dropped
# baseline (speedup 1.0000x reference)
.LBB0_3761:
	s_add_i32 s0, s51, 3
	s_sub_i32 s1, s0, s48
	s_min_u32 s2, s0, s1
	s_lshl_b64 s[0:1], s[2:3], 13
	s_waitcnt lgkmcnt(0)
	s_barrier
	s_waitcnt vmcnt(3)
	ds_write_b128 v199, v[124:127] offset:16384
	s_waitcnt vmcnt(2)
	ds_write_b128 v199, v[128:131] offset:24576
	v_lshl_add_u64 v[6:7], v[180:181], 0, s[0:1]
	v_lshl_add_u64 v[8:9], v[182:183], 0, s[0:1]
	global_load_dwordx4 v[124:127], v[6:7], off
	global_load_dwordx4 v[128:131], v[8:9], off
	s_cmp_gt_u32 s51, s47
	s_cbranch_scc1 .LBB0_3765
	ds_read_b128 v[6:9], v200
	ds_read_b128 v[10:13], v200 offset:512
	v_lshrrev_b32_e32 v1, v160, v152
	v_lshrrev_b32_e32 v14, v160, v153
	v_bitop3_b32 v228, v1, s27, v1 bitop3:0xc
	v_bitop3_b32 v229, v1, s28, v1 bitop3:0xc
	v_bitop3_b32 v230, v1, s29, v1 bitop3:0xc
	v_bitop3_b32 v231, v1, s30, v1 bitop3:0xc
	s_waitcnt lgkmcnt(1)
	v_mfma_f32_32x32x16_bf16 v[80:95], v[6:9], v[144:147], v[64:79]
	v_mul_u32_u24_e32 v228, 0xf000, v228
	v_mul_u32_u24_e32 v229, 0x7800, v229
	v_mul_u32_u24_e32 v230, 0x3c00, v230
	v_mul_u32_u24_e32 v231, 0x1e00, v231
	s_waitcnt lgkmcnt(0)
	v_mfma_f32_32x32x16_bf16 v[96:111], v[10:13], v[144:147], v[64:79]
	ds_read_b128 v[6:9], v200 offset:2048
	ds_read_b128 v[10:13], v200 offset:2560
	v_bitop3_b32 v232, v14, s27, v14 bitop3:0xc
	v_bitop3_b32 v233, v14, s28, v14 bitop3:0xc
	v_bitop3_b32 v234, v14, s29, v14 bitop3:0xc
	v_bitop3_b32 v235, v14, s30, v14 bitop3:0xc
	v_mul_u32_u24_e32 v232, 0xf000, v232
	v_mul_u32_u24_e32 v233, 0x7800, v233
	v_mul_u32_u24_e32 v234, 0x3c00, v234
	v_mul_u32_u24_e32 v235, 0x1e00, v235
	s_waitcnt lgkmcnt(1)
	v_mfma_f32_32x32x16_bf16 v[80:95], v[6:9], v[136:139], v[80:95]
	v_bitop3_b32 v236, v1, s31, v1 bitop3:0xc
	v_bitop3_b32 v237, v1, s33, v1 bitop3:0xc
	v_bitop3_b32 v238, v1, s34, v1 bitop3:0xc
	v_bitop3_b32 v239, v1, s35, v1 bitop3:0xc
	s_waitcnt lgkmcnt(0)
	v_mfma_f32_32x32x16_bf16 v[96:111], v[10:13], v[136:139], v[96:111]
	ds_read_b128 v[6:9], v200 offset:4096
	ds_read_b128 v[10:13], v200 offset:4608
	v_mul_u32_u24_e32 v236, 0xf00, v236
	v_mul_u32_u24_e32 v237, 0x780, v237
	v_mul_u32_u24_e32 v238, 0x3c0, v238
	v_mul_u32_u24_e32 v239, 0x1e0, v239
	v_bitop3_b32 v224, v14, s31, v14 bitop3:0xc
	v_bitop3_b32 v225, v14, s33, v14 bitop3:0xc
	v_bitop3_b32 v226, v14, s34, v14 bitop3:0xc
	v_bitop3_b32 v227, v14, s35, v14 bitop3:0xc
	s_waitcnt lgkmcnt(1)
	v_mfma_f32_32x32x16_bf16 v[80:95], v[6:9], v[140:143], v[80:95]
	v_mul_u32_u24_e32 v224, 0xf00, v224
	v_mul_u32_u24_e32 v225, 0x780, v225
	v_mul_u32_u24_e32 v226, 0x3c0, v226
	v_mul_u32_u24_e32 v227, 0x1e0, v227
	s_waitcnt lgkmcnt(0)
	v_mfma_f32_32x32x16_bf16 v[96:111], v[10:13], v[140:143], v[96:111]
	ds_read_b128 v[6:9], v200 offset:6144
	ds_read_b128 v[10:13], v200 offset:6656
	s_xor_b64 s[4:5], s[20:21], -1
	s_waitcnt lgkmcnt(1)
	v_mfma_f32_32x32x16_bf16 v[80:95], v[6:9], v[148:151], v[80:95]
	s_waitcnt lgkmcnt(0)
	v_mfma_f32_32x32x16_bf16 v[96:111], v[10:13], v[148:151], v[96:111]
	v_mfma_f32_32x32x16_bf16 v[80:95], v[112:115], v[228:231], v[80:95]
	v_mfma_f32_32x32x16_bf16 v[96:111], v[112:115], v[232:235], v[96:111]
	v_mfma_f32_32x32x16_bf16 v[80:95], v[116:119], v[236:239], v[80:95]
	v_mfma_f32_32x32x16_bf16 v[96:111], v[116:119], v[224:227], v[96:111]
	s_nop 15
	s_nop 7
	v_max3_f32 v1, v80, v81, v82
	v_max3_f32 v6, v83, v84, v85
	v_max3_f32 v1, v1, v86, v87
	v_max3_f32 v6, v6, v88, v89
	v_max3_f32 v1, v1, v90, v91
	v_max3_f32 v6, v6, v92, v93
	v_max3_f32 v1, v1, v94, v95
	v_max_f32 v1, v1, v6
	s_nop 0
	v_max3_f32 v7, v96, v97, v98
	v_max3_f32 v6, v99, v100, v101
	v_max3_f32 v7, v7, v102, v103
	v_max3_f32 v6, v6, v104, v105
	v_max3_f32 v7, v7, v106, v107
	v_max3_f32 v6, v6, v108, v109
	v_max3_f32 v7, v7, v110, v111
	v_max3_f32 v7, v7, v6, v1
	s_nop 0
	v_mov_b32_e32 v1, v7
	s_nop 1
	v_permlane32_swap_b32_e32 v7, v1
	v_max_f32_e32 v1, v7, v1
	v_cmp_lt_f32_e64 s[0:1], s36, v1
	s_and_b64 s[10:11], s[0:1], s[4:5]
	v_cmp_lt_f32_e32 vcc, s37, v1
	s_or_b64 s[4:5], vcc, s[10:11]
	s_and_b64 vcc, exec, s[4:5]
	s_cbranch_vccz .LBB0_3764
	v_cndmask_b32_e64 v6, 0, v1, s[4:5]
	v_exp_f32_e64 v1, -v6
	v_add_f32_e32 v171, v171, v6
	s_or_b64 s[0:1], s[20:21], s[0:1]
	v_xor_b32_e32 v64, 0x80000000, v171
	v_cndmask_b32_e64 v8, v1, 1.0, s[10:11]
	s_andn2_b64 s[4:5], s[20:21], exec
	s_and_b64 s[0:1], s[0:1], exec
	v_pk_add_f32 v[80:81], v[80:81], v[6:7] op_sel_hi:[1,0] neg_lo:[0,1] neg_hi:[0,1]
	v_pk_add_f32 v[96:97], v[96:97], v[6:7] op_sel_hi:[1,0] neg_lo:[0,1] neg_hi:[0,1]
	v_pk_add_f32 v[82:83], v[82:83], v[6:7] op_sel_hi:[1,0] neg_lo:[0,1] neg_hi:[0,1]
	v_pk_add_f32 v[98:99], v[98:99], v[6:7] op_sel_hi:[1,0] neg_lo:[0,1] neg_hi:[0,1]
	v_pk_add_f32 v[84:85], v[84:85], v[6:7] op_sel_hi:[1,0] neg_lo:[0,1] neg_hi:[0,1]
	v_pk_add_f32 v[100:101], v[100:101], v[6:7] op_sel_hi:[1,0] neg_lo:[0,1] neg_hi:[0,1]
	v_pk_add_f32 v[86:87], v[86:87], v[6:7] op_sel_hi:[1,0] neg_lo:[0,1] neg_hi:[0,1]
	v_pk_add_f32 v[102:103], v[102:103], v[6:7] op_sel_hi:[1,0] neg_lo:[0,1] neg_hi:[0,1]
	v_pk_add_f32 v[88:89], v[88:89], v[6:7] op_sel_hi:[1,0] neg_lo:[0,1] neg_hi:[0,1]
	v_pk_add_f32 v[104:105], v[104:105], v[6:7] op_sel_hi:[1,0] neg_lo:[0,1] neg_hi:[0,1]
	v_pk_add_f32 v[90:91], v[90:91], v[6:7] op_sel_hi:[1,0] neg_lo:[0,1] neg_hi:[0,1]
	v_pk_add_f32 v[106:107], v[106:107], v[6:7] op_sel_hi:[1,0] neg_lo:[0,1] neg_hi:[0,1]
	v_pk_add_f32 v[92:93], v[92:93], v[6:7] op_sel_hi:[1,0] neg_lo:[0,1] neg_hi:[0,1]
	v_pk_add_f32 v[108:109], v[108:109], v[6:7] op_sel_hi:[1,0] neg_lo:[0,1] neg_hi:[0,1]
	v_pk_add_f32 v[94:95], v[94:95], v[6:7] op_sel_hi:[1,0] neg_lo:[0,1] neg_hi:[0,1]
	v_pk_add_f32 v[110:111], v[110:111], v[6:7] op_sel_hi:[1,0] neg_lo:[0,1] neg_hi:[0,1]
	v_mov_b32_e32 v65, v64
	v_mov_b32_e32 v66, v64
	v_mov_b32_e32 v67, v64
	v_mov_b32_e32 v68, v64
	v_mov_b32_e32 v69, v64
	v_mov_b32_e32 v70, v64
	v_mov_b32_e32 v71, v64
	v_mov_b32_e32 v72, v64
	v_mov_b32_e32 v73, v64
	v_mov_b32_e32 v74, v64
	v_mov_b32_e32 v75, v64
	v_mov_b32_e32 v76, v64
	v_mov_b32_e32 v77, v64
	v_mov_b32_e32 v78, v64
	v_mov_b32_e32 v79, v64
	v_pk_mul_f32 v[30:31], v[30:31], v[8:9] op_sel_hi:[1,0]
	v_pk_mul_f32 v[28:29], v[28:29], v[8:9] op_sel_hi:[1,0]
	v_pk_mul_f32 v[26:27], v[26:27], v[8:9] op_sel_hi:[1,0]
	v_pk_mul_f32 v[24:25], v[24:25], v[8:9] op_sel_hi:[1,0]
	v_pk_mul_f32 v[22:23], v[22:23], v[8:9] op_sel_hi:[1,0]
	v_pk_mul_f32 v[20:21], v[20:21], v[8:9] op_sel_hi:[1,0]
	v_pk_mul_f32 v[18:19], v[18:19], v[8:9] op_sel_hi:[1,0]
	v_pk_mul_f32 v[16:17], v[16:17], v[8:9] op_sel_hi:[1,0]
	v_pk_mul_f32 v[46:47], v[46:47], v[8:9] op_sel_hi:[1,0]
	v_pk_mul_f32 v[44:45], v[44:45], v[8:9] op_sel_hi:[1,0]
	v_pk_mul_f32 v[42:43], v[42:43], v[8:9] op_sel_hi:[1,0]
	v_pk_mul_f32 v[40:41], v[40:41], v[8:9] op_sel_hi:[1,0]
	v_pk_mul_f32 v[38:39], v[38:39], v[8:9] op_sel_hi:[1,0]
	v_pk_mul_f32 v[36:37], v[36:37], v[8:9] op_sel_hi:[1,0]
	v_pk_mul_f32 v[34:35], v[34:35], v[8:9] op_sel_hi:[1,0]
	v_pk_mul_f32 v[32:33], v[32:33], v[8:9] op_sel_hi:[1,0]
	v_pk_mul_f32 v[62:63], v[62:63], v[8:9] op_sel_hi:[1,0]
	v_pk_mul_f32 v[60:61], v[60:61], v[8:9] op_sel_hi:[1,0]
	v_pk_mul_f32 v[58:59], v[58:59], v[8:9] op_sel_hi:[1,0]
	v_pk_mul_f32 v[56:57], v[56:57], v[8:9] op_sel_hi:[1,0]
	v_pk_mul_f32 v[54:55], v[54:55], v[8:9] op_sel_hi:[1,0]
	v_pk_mul_f32 v[52:53], v[52:53], v[8:9] op_sel_hi:[1,0]
	v_pk_mul_f32 v[50:51], v[50:51], v[8:9] op_sel_hi:[1,0]
	v_pk_mul_f32 v[48:49], v[48:49], v[8:9] op_sel_hi:[1,0]
	s_or_b64 s[20:21], s[4:5], s[0:1]

.LBB0_3765:
	s_cmp_ge_u32 s51, s46
	s_cselect_b32 s0, s49, 4
	s_add_i32 s0, s0, s51
	s_ashr_i32 s1, s0, 31
	s_lshl_b64 s[0:1], s[0:1], 13
	s_waitcnt lgkmcnt(0)
	s_barrier
	s_waitcnt vmcnt(3)
	ds_write_b128 v199, v[120:123]
	s_waitcnt vmcnt(2)
	ds_write_b128 v199, v[132:135] offset:8192
	v_lshl_add_u64 v[6:7], v[180:181], 0, s[0:1]
	v_lshl_add_u64 v[8:9], v[182:183], 0, s[0:1]
	global_load_dwordx4 v[120:123], v[6:7], off
	global_load_dwordx4 v[132:135], v[8:9], off
	s_cmp_ge_u32 s51, s47
	s_cbranch_scc1 .LBB0_3770
	ds_read_b128 v[6:9], v200 offset:16384
	ds_read_b128 v[10:13], v200 offset:16896
	v_lshrrev_b32_e32 v1, v160, v154
	v_lshrrev_b32_e32 v14, v160, v155
	v_bitop3_b32 v228, v1, s27, v1 bitop3:0xc
	v_bitop3_b32 v229, v1, s28, v1 bitop3:0xc
	v_bitop3_b32 v230, v1, s29, v1 bitop3:0xc
	v_bitop3_b32 v231, v1, s30, v1 bitop3:0xc
	s_waitcnt lgkmcnt(1)
	v_mfma_f32_32x32x16_bf16 v[80:95], v[6:9], v[144:147], v[64:79]
	v_mul_u32_u24_e32 v228, 0xf000, v228
	v_mul_u32_u24_e32 v229, 0x7800, v229
	v_mul_u32_u24_e32 v230, 0x3c00, v230
	v_mul_u32_u24_e32 v231, 0x1e00, v231
	s_waitcnt lgkmcnt(0)
	v_mfma_f32_32x32x16_bf16 v[96:111], v[10:13], v[144:147], v[64:79]
	ds_read_b128 v[6:9], v200 offset:18432
	ds_read_b128 v[10:13], v200 offset:18944
	v_bitop3_b32 v232, v14, s27, v14 bitop3:0xc
	v_bitop3_b32 v233, v14, s28, v14 bitop3:0xc
	v_bitop3_b32 v234, v14, s29, v14 bitop3:0xc
	v_bitop3_b32 v235, v14, s30, v14 bitop3:0xc
	v_mul_u32_u24_e32 v232, 0xf000, v232
	v_mul_u32_u24_e32 v233, 0x7800, v233
	v_mul_u32_u24_e32 v234, 0x3c00, v234
	v_mul_u32_u24_e32 v235, 0x1e00, v235
	s_waitcnt lgkmcnt(1)
	v_mfma_f32_32x32x16_bf16 v[80:95], v[6:9], v[136:139], v[80:95]
	v_bitop3_b32 v236, v1, s31, v1 bitop3:0xc
	v_bitop3_b32 v237, v1, s33, v1 bitop3:0xc
	v_bitop3_b32 v238, v1, s34, v1 bitop3:0xc
	v_bitop3_b32 v239, v1, s35, v1 bitop3:0xc
	s_waitcnt lgkmcnt(0)
	v_mfma_f32_32x32x16_bf16 v[96:111], v[10:13], v[136:139], v[96:111]
	ds_read_b128 v[6:9], v200 offset:20480
	ds_read_b128 v[10:13], v200 offset:20992
	v_mul_u32_u24_e32 v236, 0xf00, v236
	v_mul_u32_u24_e32 v237, 0x780, v237
	v_mul_u32_u24_e32 v238, 0x3c0, v238
	v_mul_u32_u24_e32 v239, 0x1e0, v239
	v_bitop3_b32 v224, v14, s31, v14 bitop3:0xc
	v_bitop3_b32 v225, v14, s33, v14 bitop3:0xc
	v_bitop3_b32 v226, v14, s34, v14 bitop3:0xc
	v_bitop3_b32 v227, v14, s35, v14 bitop3:0xc
	s_waitcnt lgkmcnt(1)
	v_mfma_f32_32x32x16_bf16 v[80:95], v[6:9], v[140:143], v[80:95]
	v_mul_u32_u24_e32 v224, 0xf00, v224
	v_mul_u32_u24_e32 v225, 0x780, v225
	v_mul_u32_u24_e32 v226, 0x3c0, v226
	v_mul_u32_u24_e32 v227, 0x1e0, v227
	s_waitcnt lgkmcnt(0)
	v_mfma_f32_32x32x16_bf16 v[96:111], v[10:13], v[140:143], v[96:111]
	ds_read_b128 v[6:9], v200 offset:22528
	ds_read_b128 v[10:13], v200 offset:23040
	s_xor_b64 s[4:5], s[20:21], -1
	s_and_b64 vcc, exec, s[4:5]
	s_waitcnt lgkmcnt(1)
	v_mfma_f32_32x32x16_bf16 v[80:95], v[6:9], v[148:151], v[80:95]
	s_waitcnt lgkmcnt(0)
	v_mfma_f32_32x32x16_bf16 v[96:111], v[10:13], v[148:151], v[96:111]
	v_mfma_f32_32x32x16_bf16 v[80:95], v[112:115], v[228:231], v[80:95]
	v_mfma_f32_32x32x16_bf16 v[96:111], v[112:115], v[232:235], v[96:111]
	v_mfma_f32_32x32x16_bf16 v[80:95], v[116:119], v[236:239], v[80:95]
	v_mfma_f32_32x32x16_bf16 v[96:111], v[116:119], v[224:227], v[96:111]
	s_cbranch_vccz .LBB0_3769
	s_nop 15
	s_nop 7
	v_max3_f32 v1, v80, v81, v82
	v_max3_f32 v6, v83, v84, v85
	v_max3_f32 v1, v1, v86, v87
	v_max3_f32 v6, v6, v88, v89
	v_max3_f32 v1, v1, v90, v91
	v_max3_f32 v6, v6, v92, v93
	v_max3_f32 v1, v1, v94, v95
	v_max_f32 v1, v1, v6
	s_nop 0
	v_max3_f32 v7, v96, v97, v98
	v_max3_f32 v6, v99, v100, v101
	v_max3_f32 v7, v7, v102, v103
	v_max3_f32 v6, v6, v104, v105
	v_max3_f32 v7, v7, v106, v107
	v_max3_f32 v6, v6, v108, v109
	v_max3_f32 v7, v7, v110, v111
	v_max3_f32 v7, v7, v6, v1
	s_nop 0
	v_mov_b32_e32 v1, v7
	s_nop 1
	v_permlane32_swap_b32_e32 v7, v1
	v_max_f32_e32 v1, v7, v1
	v_cmp_lt_f32_e64 s[0:1], s36, v1
	s_and_b64 s[10:11], s[0:1], s[4:5]
	v_cmp_lt_f32_e32 vcc, s37, v1
	s_or_b64 s[4:5], vcc, s[10:11]
	s_and_b64 vcc, exec, s[4:5]
	s_cbranch_vccz .LBB0_3769
	v_cndmask_b32_e64 v1, 0, v1, s[4:5]
	v_exp_f32_e64 v6, -v1
	v_add_f32_e32 v171, v171, v1
	s_or_b64 s[0:1], s[20:21], s[0:1]
	v_xor_b32_e32 v64, 0x80000000, v171
	v_cndmask_b32_e64 v6, v6, 1.0, s[10:11]
	s_andn2_b64 s[4:5], s[20:21], exec
	s_and_b64 s[0:1], s[0:1], exec
	v_mov_b32_e32 v65, v64
	v_mov_b32_e32 v66, v64
	v_mov_b32_e32 v67, v64
	v_mov_b32_e32 v68, v64
	v_mov_b32_e32 v69, v64
	v_mov_b32_e32 v70, v64
	v_mov_b32_e32 v71, v64
	v_mov_b32_e32 v72, v64
	v_mov_b32_e32 v73, v64
	v_mov_b32_e32 v74, v64
	v_mov_b32_e32 v75, v64
	v_mov_b32_e32 v76, v64
	v_mov_b32_e32 v77, v64
	v_mov_b32_e32 v78, v64
	v_mov_b32_e32 v79, v64
	v_pk_mul_f32 v[30:31], v[30:31], v[6:7] op_sel_hi:[1,0]
	v_pk_mul_f32 v[28:29], v[28:29], v[6:7] op_sel_hi:[1,0]
	v_pk_mul_f32 v[26:27], v[26:27], v[6:7] op_sel_hi:[1,0]
	v_pk_mul_f32 v[24:25], v[24:25], v[6:7] op_sel_hi:[1,0]
	v_pk_mul_f32 v[22:23], v[22:23], v[6:7] op_sel_hi:[1,0]
	v_pk_mul_f32 v[20:21], v[20:21], v[6:7] op_sel_hi:[1,0]
	v_pk_mul_f32 v[18:19], v[18:19], v[6:7] op_sel_hi:[1,0]
	v_pk_mul_f32 v[16:17], v[16:17], v[6:7] op_sel_hi:[1,0]
	v_pk_mul_f32 v[46:47], v[46:47], v[6:7] op_sel_hi:[1,0]
	v_pk_mul_f32 v[44:45], v[44:45], v[6:7] op_sel_hi:[1,0]
	v_pk_mul_f32 v[42:43], v[42:43], v[6:7] op_sel_hi:[1,0]
	v_pk_mul_f32 v[40:41], v[40:41], v[6:7] op_sel_hi:[1,0]
	v_pk_mul_f32 v[38:39], v[38:39], v[6:7] op_sel_hi:[1,0]
	v_pk_mul_f32 v[36:37], v[36:37], v[6:7] op_sel_hi:[1,0]
	v_pk_mul_f32 v[34:35], v[34:35], v[6:7] op_sel_hi:[1,0]
	v_pk_mul_f32 v[32:33], v[32:33], v[6:7] op_sel_hi:[1,0]
	v_pk_mul_f32 v[62:63], v[62:63], v[6:7] op_sel_hi:[1,0]
	v_pk_mul_f32 v[60:61], v[60:61], v[6:7] op_sel_hi:[1,0]
	v_pk_mul_f32 v[58:59], v[58:59], v[6:7] op_sel_hi:[1,0]
	v_pk_mul_f32 v[56:57], v[56:57], v[6:7] op_sel_hi:[1,0]
	v_pk_mul_f32 v[54:55], v[54:55], v[6:7] op_sel_hi:[1,0]
	v_pk_mul_f32 v[52:53], v[52:53], v[6:7] op_sel_hi:[1,0]
	v_pk_mul_f32 v[50:51], v[50:51], v[6:7] op_sel_hi:[1,0]
	v_pk_mul_f32 v[48:49], v[48:49], v[6:7] op_sel_hi:[1,0]
	v_sub_f32_e32 v95, v95, v1
	v_sub_f32_e32 v94, v94, v1
	v_sub_f32_e32 v93, v93, v1
	v_sub_f32_e32 v92, v92, v1
	v_sub_f32_e32 v91, v91, v1
	v_sub_f32_e32 v90, v90, v1
	v_sub_f32_e32 v89, v89, v1
	v_sub_f32_e32 v88, v88, v1
	v_sub_f32_e32 v87, v87, v1
	v_sub_f32_e32 v86, v86, v1
	v_sub_f32_e32 v85, v85, v1
	v_sub_f32_e32 v84, v84, v1
	v_sub_f32_e32 v83, v83, v1
	v_sub_f32_e32 v82, v82, v1
	v_sub_f32_e32 v81, v81, v1
	v_sub_f32_e32 v80, v80, v1
	v_sub_f32_e32 v111, v111, v1
	v_sub_f32_e32 v110, v110, v1
	v_sub_f32_e32 v109, v109, v1
	v_sub_f32_e32 v108, v108, v1
	v_sub_f32_e32 v107, v107, v1
	v_sub_f32_e32 v106, v106, v1
	v_sub_f32_e32 v105, v105, v1
	v_sub_f32_e32 v104, v104, v1
	v_sub_f32_e32 v103, v103, v1
	v_sub_f32_e32 v102, v102, v1
	v_sub_f32_e32 v101, v101, v1
	v_sub_f32_e32 v100, v100, v1
	v_sub_f32_e32 v99, v99, v1
	v_sub_f32_e32 v98, v98, v1
	v_sub_f32_e32 v97, v97, v1
	v_sub_f32_e32 v96, v96, v1
	s_or_b64 s[20:21], s[4:5], s[0:1]
